# act-path epilogue stores without the nt hint
# speedup vs baseline: 1.0314x; 1.0314x over previous
; #define GAS __attribute__((address_space(1)))
; __device__ __forceinline__ float fexp2(float x) { return __builtin_amdgcn_exp2f(x); }
; __device__ __forceinline__ float frcp(float x) { return __builtin_amdgcn_rcpf(x); }
; #define EPI_FOR_ROWS for (int ai = 0; ai < 2; ++ai) _Pragma("unroll") for (int m = 0; m < 4; ++m)
; __device__ __forceinline__ v4u pack8(const f32x4 a, const f32x4 b) { v4u w; w.x = cvt_pk_bf16(a[0], a[1]); w.y = cvt_pk_bf16(a[2], a[3]); w.z = cvt_pk_bf16(b[0], b[1]); w.w = cvt_pk_bf16(b[2], b[3]); return w; }
; #define NT_ST(p, v) __builtin_nontemporal_store((v), (p))
; __device__ __forceinline__ float fsigmoid(float x) { return frcp(1.0f + fexp2(-x * LOG2E)); }
;     __device__ __forceinline__ void operator()(Acc& acc, const Unit& u, int wr, int wc, int fr, int fq, LAS unsigned char* lds) const {
;     ...
;         GAS bf16* dst = (GAS bf16*)(ws + off);
; #pragma unroll
;         EPI_FOR_ROWS { const int row = row0 + ai * 128 + m * 16;
; #pragma unroll
;             for (int bj = 0; bj < 2; ++bj) { f32x4 a = acc[ai][bj][m][0], b = acc[ai][bj][m][1];
;                 if (act) {
; #pragma unroll
;                     for (int j = 0; j < 4; ++j) { const float sa = fsigmoid(a[j]), sb = fsigmoid(b[j]);
;                         a[j] = act == 1 ? a[j] * sa : fmaxf(sa, 1e-30f); b[j] = act == 1 ? b[j] * sb : fmaxf(sb, 1e-30f); } }
;                 NT_ST((GAS v4u*)(dst + (size_t)row * 1024 + cg0 + bj * 128), pack8(a, b)); } }
.LBB0_236:
	v_readlane_b32 s34, v240, 13
	v_readlane_b32 s35, v240, 12
	v_ashrrev_i32_e32 v153, 31, v152
	v_ashrrev_i32_e32 v155, 31, v154
	s_add_u32 s34, s34, s52
	s_addc_u32 s35, s35, s53
	v_lshlrev_b64 v[158:159], 11, v[154:155]
	v_lshl_add_u64 v[156:157], v[152:153], 1, s[34:35]
	s_mov_b32 s24, 0xbfb8aa3b
	s_mov_b32 s25, 0xda24260
	v_lshl_add_u64 v[158:159], v[156:157], 0, v[158:159]
	s_and_b64 vcc, exec, s[64:65]
	s_cbranch_vccnz .Lep_none
	s_and_b64 vcc, exec, s[62:63]
	s_cbranch_vccnz .Lep_silu
	v_pk_mul_f32 v[128:129], v[124:125], s[24:25] op_sel_hi:[1,0]
	v_pk_mul_f32 v[130:131], v[126:127], s[24:25] op_sel_hi:[1,0]
	v_pk_mul_f32 v[132:133], v[120:121], s[24:25] op_sel_hi:[1,0]
	v_pk_mul_f32 v[134:135], v[122:123], s[24:25] op_sel_hi:[1,0]
	v_pk_mul_f32 v[160:161], v[116:117], s[24:25] op_sel_hi:[1,0]
	v_pk_mul_f32 v[162:163], v[118:119], s[24:25] op_sel_hi:[1,0]
	v_pk_mul_f32 v[164:165], v[112:113], s[24:25] op_sel_hi:[1,0]
	v_pk_mul_f32 v[166:167], v[114:115], s[24:25] op_sel_hi:[1,0]
	v_exp_f32_e32 v128, v128
	v_exp_f32_e32 v129, v129
	v_exp_f32_e32 v130, v130
	v_exp_f32_e32 v131, v131
	v_exp_f32_e32 v132, v132
	v_exp_f32_e32 v133, v133
	v_exp_f32_e32 v134, v134
	v_exp_f32_e32 v135, v135
	v_exp_f32_e32 v160, v160
	v_exp_f32_e32 v161, v161
	v_exp_f32_e32 v162, v162
	v_exp_f32_e32 v163, v163
	v_exp_f32_e32 v164, v164
	v_exp_f32_e32 v165, v165
	v_exp_f32_e32 v166, v166
	v_exp_f32_e32 v167, v167
	v_pk_add_f32 v[128:129], v[128:129], 1.0 op_sel_hi:[1,0]
	v_pk_add_f32 v[130:131], v[130:131], 1.0 op_sel_hi:[1,0]
	v_pk_add_f32 v[132:133], v[132:133], 1.0 op_sel_hi:[1,0]
	v_pk_add_f32 v[134:135], v[134:135], 1.0 op_sel_hi:[1,0]
	v_pk_add_f32 v[160:161], v[160:161], 1.0 op_sel_hi:[1,0]
	v_pk_add_f32 v[162:163], v[162:163], 1.0 op_sel_hi:[1,0]
	v_pk_add_f32 v[164:165], v[164:165], 1.0 op_sel_hi:[1,0]
	v_pk_add_f32 v[166:167], v[166:167], 1.0 op_sel_hi:[1,0]
	v_rcp_f32_e32 v128, v128
	v_rcp_f32_e32 v129, v129
	v_rcp_f32_e32 v130, v130
	v_rcp_f32_e32 v131, v131
	v_rcp_f32_e32 v132, v132
	v_rcp_f32_e32 v133, v133
	v_rcp_f32_e32 v134, v134
	v_rcp_f32_e32 v135, v135
	v_rcp_f32_e32 v160, v160
	v_rcp_f32_e32 v161, v161
	v_rcp_f32_e32 v162, v162
	v_rcp_f32_e32 v163, v163
	v_rcp_f32_e32 v164, v164
	v_rcp_f32_e32 v165, v165
	v_rcp_f32_e32 v166, v166
	v_rcp_f32_e32 v167, v167
	v_max_f32_e32 v128, s25, v128
	v_max_f32_e32 v129, s25, v129
	v_max_f32_e32 v130, s25, v130
	v_max_f32_e32 v131, s25, v131
	v_max_f32_e32 v132, s25, v132
	v_max_f32_e32 v133, s25, v133
	v_max_f32_e32 v134, s25, v134
	v_max_f32_e32 v135, s25, v135
	v_max_f32_e32 v160, s25, v160
	v_max_f32_e32 v161, s25, v161
	v_max_f32_e32 v162, s25, v162
	v_max_f32_e32 v163, s25, v163
	v_max_f32_e32 v164, s25, v164
	v_max_f32_e32 v165, s25, v165
	v_max_f32_e32 v166, s25, v166
	v_max_f32_e32 v167, s25, v167
	v_cvt_pk_bf16_f32 v128, v128, v129
	v_cvt_pk_bf16_f32 v129, v130, v131
	v_cvt_pk_bf16_f32 v130, v132, v133
	v_cvt_pk_bf16_f32 v131, v134, v135
	v_cvt_pk_bf16_f32 v160, v160, v161
	global_store_dwordx4 v[158:159], v[128:131], off
	v_cvt_pk_bf16_f32 v161, v162, v163
	v_cvt_pk_bf16_f32 v162, v164, v165
	v_cvt_pk_bf16_f32 v163, v166, v167
	s_nop 0
	global_store_dwordx4 v[158:159], v[160:163], off offset:256
	s_mov_b64 s[34:35], 0x8000
	v_pk_mul_f32 v[128:129], v[108:109], s[24:25] op_sel_hi:[1,0]
	v_pk_mul_f32 v[130:131], v[110:111], s[24:25] op_sel_hi:[1,0]
	v_pk_mul_f32 v[132:133], v[104:105], s[24:25] op_sel_hi:[1,0]
	v_pk_mul_f32 v[134:135], v[106:107], s[24:25] op_sel_hi:[1,0]
	v_pk_mul_f32 v[160:161], v[100:101], s[24:25] op_sel_hi:[1,0]
	v_pk_mul_f32 v[162:163], v[102:103], s[24:25] op_sel_hi:[1,0]
	v_pk_mul_f32 v[164:165], v[96:97], s[24:25] op_sel_hi:[1,0]
	v_pk_mul_f32 v[166:167], v[98:99], s[24:25] op_sel_hi:[1,0]
	v_exp_f32_e32 v128, v128
	v_exp_f32_e32 v129, v129
	v_exp_f32_e32 v130, v130
	v_exp_f32_e32 v131, v131
	v_exp_f32_e32 v132, v132
	v_exp_f32_e32 v133, v133
	v_exp_f32_e32 v134, v134
	v_exp_f32_e32 v135, v135
	v_exp_f32_e32 v160, v160
	v_exp_f32_e32 v161, v161
	v_exp_f32_e32 v162, v162
	v_exp_f32_e32 v163, v163
	v_exp_f32_e32 v164, v164
	v_exp_f32_e32 v165, v165
	v_exp_f32_e32 v166, v166
	v_exp_f32_e32 v167, v167
	v_lshl_add_u64 v[168:169], v[158:159], 0, s[34:35]
	v_pk_add_f32 v[128:129], v[128:129], 1.0 op_sel_hi:[1,0]
	v_pk_add_f32 v[130:131], v[130:131], 1.0 op_sel_hi:[1,0]
	v_pk_add_f32 v[132:133], v[132:133], 1.0 op_sel_hi:[1,0]
	v_pk_add_f32 v[134:135], v[134:135], 1.0 op_sel_hi:[1,0]
	v_pk_add_f32 v[160:161], v[160:161], 1.0 op_sel_hi:[1,0]
	v_pk_add_f32 v[162:163], v[162:163], 1.0 op_sel_hi:[1,0]
	v_pk_add_f32 v[164:165], v[164:165], 1.0 op_sel_hi:[1,0]
	v_pk_add_f32 v[166:167], v[166:167], 1.0 op_sel_hi:[1,0]
	v_rcp_f32_e32 v128, v128
	v_rcp_f32_e32 v129, v129
	v_rcp_f32_e32 v130, v130
	v_rcp_f32_e32 v131, v131
	v_rcp_f32_e32 v132, v132
	v_rcp_f32_e32 v133, v133
	v_rcp_f32_e32 v134, v134
	v_rcp_f32_e32 v135, v135
	v_rcp_f32_e32 v160, v160
	v_rcp_f32_e32 v161, v161
	v_rcp_f32_e32 v162, v162
	v_rcp_f32_e32 v163, v163
	v_rcp_f32_e32 v164, v164
	v_rcp_f32_e32 v165, v165
	v_rcp_f32_e32 v166, v166
	v_rcp_f32_e32 v167, v167
	v_max_f32_e32 v128, s25, v128
	v_max_f32_e32 v129, s25, v129
	v_max_f32_e32 v130, s25, v130
	v_max_f32_e32 v131, s25, v131
	v_max_f32_e32 v132, s25, v132
	v_max_f32_e32 v133, s25, v133
	v_max_f32_e32 v134, s25, v134
	v_max_f32_e32 v135, s25, v135
	v_max_f32_e32 v160, s25, v160
	v_max_f32_e32 v161, s25, v161
	v_max_f32_e32 v162, s25, v162
	v_max_f32_e32 v163, s25, v163
	v_max_f32_e32 v164, s25, v164
	v_max_f32_e32 v165, s25, v165
	v_max_f32_e32 v166, s25, v166
	v_max_f32_e32 v167, s25, v167
	v_cvt_pk_bf16_f32 v128, v128, v129
	v_cvt_pk_bf16_f32 v129, v130, v131
; #define GAS __attribute__((address_space(1)))
; __device__ __forceinline__ float fexp2(float x) { return __builtin_amdgcn_exp2f(x); }
; __device__ __forceinline__ float frcp(float x) { return __builtin_amdgcn_rcpf(x); }
; #define EPI_FOR_ROWS for (int ai = 0; ai < 2; ++ai) _Pragma("unroll") for (int m = 0; m < 4; ++m)
; __device__ __forceinline__ v4u pack8(const f32x4 a, const f32x4 b) { v4u w; w.x = cvt_pk_bf16(a[0], a[1]); w.y = cvt_pk_bf16(a[2], a[3]); w.z = cvt_pk_bf16(b[0], b[1]); w.w = cvt_pk_bf16(b[2], b[3]); return w; }
; #define NT_ST(p, v) __builtin_nontemporal_store((v), (p))
; __device__ __forceinline__ float fsigmoid(float x) { return frcp(1.0f + fexp2(-x * LOG2E)); }
;     __device__ __forceinline__ void operator()(Acc& acc, const Unit& u, int wr, int wc, int fr, int fq, LAS unsigned char* lds) const {
;     ...
;         GAS bf16* dst = (GAS bf16*)(ws + off);
; #pragma unroll
;         EPI_FOR_ROWS { const int row = row0 + ai * 128 + m * 16;
; #pragma unroll
;             for (int bj = 0; bj < 2; ++bj) { f32x4 a = acc[ai][bj][m][0], b = acc[ai][bj][m][1];
;                 if (act) {
; #pragma unroll
;                     for (int j = 0; j < 4; ++j) { const float sa = fsigmoid(a[j]), sb = fsigmoid(b[j]);
;                         a[j] = act == 1 ? a[j] * sa : fmaxf(sa, 1e-30f); b[j] = act == 1 ? b[j] * sb : fmaxf(sb, 1e-30f); } }
;                 NT_ST((GAS v4u*)(dst + (size_t)row * 1024 + cg0 + bj * 128), pack8(a, b)); } }
	v_cvt_pk_bf16_f32 v130, v132, v133
	v_cvt_pk_bf16_f32 v131, v134, v135
	v_cvt_pk_bf16_f32 v160, v160, v161
	global_store_dwordx4 v[168:169], v[128:131], off
	v_cvt_pk_bf16_f32 v161, v162, v163
	v_cvt_pk_bf16_f32 v162, v164, v165
	v_cvt_pk_bf16_f32 v163, v166, v167
	s_nop 0
	global_store_dwordx4 v[168:169], v[160:163], off offset:256
	s_mov_b64 s[34:35], 0x10000
	v_pk_mul_f32 v[128:129], v[92:93], s[24:25] op_sel_hi:[1,0]
	v_pk_mul_f32 v[130:131], v[94:95], s[24:25] op_sel_hi:[1,0]
	v_pk_mul_f32 v[132:133], v[88:89], s[24:25] op_sel_hi:[1,0]
	v_pk_mul_f32 v[134:135], v[90:91], s[24:25] op_sel_hi:[1,0]
	v_pk_mul_f32 v[160:161], v[84:85], s[24:25] op_sel_hi:[1,0]
	v_pk_mul_f32 v[162:163], v[86:87], s[24:25] op_sel_hi:[1,0]
	v_pk_mul_f32 v[164:165], v[80:81], s[24:25] op_sel_hi:[1,0]
	v_pk_mul_f32 v[166:167], v[82:83], s[24:25] op_sel_hi:[1,0]
	v_exp_f32_e32 v128, v128
	v_exp_f32_e32 v129, v129
	v_exp_f32_e32 v130, v130
	v_exp_f32_e32 v131, v131
	v_exp_f32_e32 v132, v132
	v_exp_f32_e32 v133, v133
	v_exp_f32_e32 v134, v134
	v_exp_f32_e32 v135, v135
	v_exp_f32_e32 v160, v160
	v_exp_f32_e32 v161, v161
	v_exp_f32_e32 v162, v162
	v_exp_f32_e32 v163, v163
	v_exp_f32_e32 v164, v164
	v_exp_f32_e32 v165, v165
	v_exp_f32_e32 v166, v166
	v_exp_f32_e32 v167, v167
	v_lshl_add_u64 v[170:171], v[158:159], 0, s[34:35]
	v_pk_add_f32 v[128:129], v[128:129], 1.0 op_sel_hi:[1,0]
	v_pk_add_f32 v[130:131], v[130:131], 1.0 op_sel_hi:[1,0]
	v_pk_add_f32 v[132:133], v[132:133], 1.0 op_sel_hi:[1,0]
	v_pk_add_f32 v[134:135], v[134:135], 1.0 op_sel_hi:[1,0]
	v_pk_add_f32 v[160:161], v[160:161], 1.0 op_sel_hi:[1,0]
	v_pk_add_f32 v[162:163], v[162:163], 1.0 op_sel_hi:[1,0]
	v_pk_add_f32 v[164:165], v[164:165], 1.0 op_sel_hi:[1,0]
	v_pk_add_f32 v[166:167], v[166:167], 1.0 op_sel_hi:[1,0]
	v_rcp_f32_e32 v128, v128
	v_rcp_f32_e32 v129, v129
	v_rcp_f32_e32 v130, v130
	v_rcp_f32_e32 v131, v131
	v_rcp_f32_e32 v132, v132
	v_rcp_f32_e32 v133, v133
	v_rcp_f32_e32 v134, v134
	v_rcp_f32_e32 v135, v135
	v_rcp_f32_e32 v160, v160
	v_rcp_f32_e32 v161, v161
	v_rcp_f32_e32 v162, v162
	v_rcp_f32_e32 v163, v163
	v_rcp_f32_e32 v164, v164
	v_rcp_f32_e32 v165, v165
	v_rcp_f32_e32 v166, v166
	v_rcp_f32_e32 v167, v167
	v_max_f32_e32 v128, s25, v128
	v_max_f32_e32 v129, s25, v129
	v_max_f32_e32 v130, s25, v130
	v_max_f32_e32 v131, s25, v131
	v_max_f32_e32 v132, s25, v132
	v_max_f32_e32 v133, s25, v133
	v_max_f32_e32 v134, s25, v134
	v_max_f32_e32 v135, s25, v135
	v_max_f32_e32 v160, s25, v160
	v_max_f32_e32 v161, s25, v161
	v_max_f32_e32 v162, s25, v162
	v_max_f32_e32 v163, s25, v163
	v_max_f32_e32 v164, s25, v164
	v_max_f32_e32 v165, s25, v165
	v_max_f32_e32 v166, s25, v166
	v_max_f32_e32 v167, s25, v167
	v_cvt_pk_bf16_f32 v128, v128, v129
	v_cvt_pk_bf16_f32 v129, v130, v131
	v_cvt_pk_bf16_f32 v130, v132, v133
	v_cvt_pk_bf16_f32 v131, v134, v135
	v_cvt_pk_bf16_f32 v160, v160, v161
	global_store_dwordx4 v[170:171], v[128:131], off
	v_cvt_pk_bf16_f32 v161, v162, v163
	v_cvt_pk_bf16_f32 v162, v164, v165
	v_cvt_pk_bf16_f32 v163, v166, v167
	s_nop 0
	global_store_dwordx4 v[170:171], v[160:163], off offset:256
	s_mov_b64 s[34:35], 0x18000
	v_pk_mul_f32 v[128:129], v[76:77], s[24:25] op_sel_hi:[1,0]
	v_pk_mul_f32 v[130:131], v[78:79], s[24:25] op_sel_hi:[1,0]
	v_pk_mul_f32 v[132:133], v[72:73], s[24:25] op_sel_hi:[1,0]
	v_pk_mul_f32 v[134:135], v[74:75], s[24:25] op_sel_hi:[1,0]
	v_pk_mul_f32 v[160:161], v[68:69], s[24:25] op_sel_hi:[1,0]
	v_pk_mul_f32 v[162:163], v[70:71], s[24:25] op_sel_hi:[1,0]
	v_pk_mul_f32 v[164:165], v[64:65], s[24:25] op_sel_hi:[1,0]
	v_pk_mul_f32 v[166:167], v[66:67], s[24:25] op_sel_hi:[1,0]
	v_exp_f32_e32 v128, v128
	v_exp_f32_e32 v129, v129
	v_exp_f32_e32 v130, v130
	v_exp_f32_e32 v131, v131
	v_exp_f32_e32 v132, v132
	v_exp_f32_e32 v133, v133
	v_exp_f32_e32 v134, v134
	v_exp_f32_e32 v135, v135
	v_exp_f32_e32 v160, v160
	v_exp_f32_e32 v161, v161
	v_exp_f32_e32 v162, v162
	v_exp_f32_e32 v163, v163
	v_exp_f32_e32 v164, v164
	v_exp_f32_e32 v165, v165
	v_exp_f32_e32 v166, v166
	v_exp_f32_e32 v167, v167
	v_lshl_add_u64 v[168:169], v[158:159], 0, s[34:35]
	v_pk_add_f32 v[128:129], v[128:129], 1.0 op_sel_hi:[1,0]
	v_pk_add_f32 v[130:131], v[130:131], 1.0 op_sel_hi:[1,0]
	v_pk_add_f32 v[132:133], v[132:133], 1.0 op_sel_hi:[1,0]
	v_pk_add_f32 v[134:135], v[134:135], 1.0 op_sel_hi:[1,0]
	v_pk_add_f32 v[160:161], v[160:161], 1.0 op_sel_hi:[1,0]
	v_pk_add_f32 v[162:163], v[162:163], 1.0 op_sel_hi:[1,0]
	v_pk_add_f32 v[164:165], v[164:165], 1.0 op_sel_hi:[1,0]
	v_pk_add_f32 v[166:167], v[166:167], 1.0 op_sel_hi:[1,0]
	v_rcp_f32_e32 v128, v128
	v_rcp_f32_e32 v129, v129
	v_rcp_f32_e32 v130, v130
	v_rcp_f32_e32 v131, v131
	v_rcp_f32_e32 v132, v132
	v_rcp_f32_e32 v133, v133
	v_rcp_f32_e32 v134, v134
	v_rcp_f32_e32 v135, v135
	v_rcp_f32_e32 v160, v160
	v_rcp_f32_e32 v161, v161
	v_rcp_f32_e32 v162, v162
	v_rcp_f32_e32 v163, v163
	v_rcp_f32_e32 v164, v164
	v_rcp_f32_e32 v165, v165
	v_rcp_f32_e32 v166, v166
	v_rcp_f32_e32 v167, v167
	v_max_f32_e32 v128, s25, v128
	v_max_f32_e32 v129, s25, v129
	v_max_f32_e32 v130, s25, v130
	v_max_f32_e32 v131, s25, v131
	v_max_f32_e32 v132, s25, v132
	v_max_f32_e32 v133, s25, v133
	v_max_f32_e32 v134, s25, v134
	v_max_f32_e32 v135, s25, v135
	v_max_f32_e32 v160, s25, v160
	v_max_f32_e32 v161, s25, v161
	v_max_f32_e32 v162, s25, v162
	v_max_f32_e32 v163, s25, v163
	v_max_f32_e32 v164, s25, v164
	v_max_f32_e32 v165, s25, v165
	v_max_f32_e32 v166, s25, v166
	v_max_f32_e32 v167, s25, v167
	v_cvt_pk_bf16_f32 v128, v128, v129
	v_cvt_pk_bf16_f32 v129, v130, v131
	v_cvt_pk_bf16_f32 v130, v132, v133
	v_cvt_pk_bf16_f32 v131, v134, v135
	v_cvt_pk_bf16_f32 v160, v160, v161
; #define GAS __attribute__((address_space(1)))
; __device__ __forceinline__ float fexp2(float x) { return __builtin_amdgcn_exp2f(x); }
; __device__ __forceinline__ float frcp(float x) { return __builtin_amdgcn_rcpf(x); }
; #define EPI_FOR_ROWS for (int ai = 0; ai < 2; ++ai) _Pragma("unroll") for (int m = 0; m < 4; ++m)
; __device__ __forceinline__ v4u pack8(const f32x4 a, const f32x4 b) { v4u w; w.x = cvt_pk_bf16(a[0], a[1]); w.y = cvt_pk_bf16(a[2], a[3]); w.z = cvt_pk_bf16(b[0], b[1]); w.w = cvt_pk_bf16(b[2], b[3]); return w; }
; #define NT_ST(p, v) __builtin_nontemporal_store((v), (p))
; __device__ __forceinline__ float fsigmoid(float x) { return frcp(1.0f + fexp2(-x * LOG2E)); }
;     __device__ __forceinline__ void operator()(Acc& acc, const Unit& u, int wr, int wc, int fr, int fq, LAS unsigned char* lds) const {
;     ...
;         GAS bf16* dst = (GAS bf16*)(ws + off);
; #pragma unroll
;         EPI_FOR_ROWS { const int row = row0 + ai * 128 + m * 16;
; #pragma unroll
;             for (int bj = 0; bj < 2; ++bj) { f32x4 a = acc[ai][bj][m][0], b = acc[ai][bj][m][1];
;                 if (act) {
; #pragma unroll
;                     for (int j = 0; j < 4; ++j) { const float sa = fsigmoid(a[j]), sb = fsigmoid(b[j]);
;                         a[j] = act == 1 ? a[j] * sa : fmaxf(sa, 1e-30f); b[j] = act == 1 ? b[j] * sb : fmaxf(sb, 1e-30f); } }
;                 NT_ST((GAS v4u*)(dst + (size_t)row * 1024 + cg0 + bj * 128), pack8(a, b)); } }
	global_store_dwordx4 v[168:169], v[128:131], off
	v_cvt_pk_bf16_f32 v161, v162, v163
	v_cvt_pk_bf16_f32 v162, v164, v165
	v_cvt_pk_bf16_f32 v163, v166, v167
	s_nop 0
	global_store_dwordx4 v[168:169], v[160:163], off offset:256
	s_mov_b64 s[34:35], 0x40000
	v_pk_mul_f32 v[128:129], v[60:61], s[24:25] op_sel_hi:[1,0]
	v_pk_mul_f32 v[130:131], v[62:63], s[24:25] op_sel_hi:[1,0]
	v_pk_mul_f32 v[132:133], v[56:57], s[24:25] op_sel_hi:[1,0]
	v_pk_mul_f32 v[134:135], v[58:59], s[24:25] op_sel_hi:[1,0]
	v_pk_mul_f32 v[160:161], v[52:53], s[24:25] op_sel_hi:[1,0]
	v_pk_mul_f32 v[162:163], v[54:55], s[24:25] op_sel_hi:[1,0]
	v_pk_mul_f32 v[164:165], v[48:49], s[24:25] op_sel_hi:[1,0]
	v_pk_mul_f32 v[166:167], v[50:51], s[24:25] op_sel_hi:[1,0]
	v_exp_f32_e32 v128, v128
	v_exp_f32_e32 v129, v129
	v_exp_f32_e32 v130, v130
	v_exp_f32_e32 v131, v131
	v_exp_f32_e32 v132, v132
	v_exp_f32_e32 v133, v133
	v_exp_f32_e32 v134, v134
	v_exp_f32_e32 v135, v135
	v_exp_f32_e32 v160, v160
	v_exp_f32_e32 v161, v161
	v_exp_f32_e32 v162, v162
	v_exp_f32_e32 v163, v163
	v_exp_f32_e32 v164, v164
	v_exp_f32_e32 v165, v165
	v_exp_f32_e32 v166, v166
	v_exp_f32_e32 v167, v167
	v_lshl_add_u64 v[170:171], v[158:159], 0, s[34:35]
	v_pk_add_f32 v[128:129], v[128:129], 1.0 op_sel_hi:[1,0]
	v_pk_add_f32 v[130:131], v[130:131], 1.0 op_sel_hi:[1,0]
	v_pk_add_f32 v[132:133], v[132:133], 1.0 op_sel_hi:[1,0]
	v_pk_add_f32 v[134:135], v[134:135], 1.0 op_sel_hi:[1,0]
	v_pk_add_f32 v[160:161], v[160:161], 1.0 op_sel_hi:[1,0]
	v_pk_add_f32 v[162:163], v[162:163], 1.0 op_sel_hi:[1,0]
	v_pk_add_f32 v[164:165], v[164:165], 1.0 op_sel_hi:[1,0]
	v_pk_add_f32 v[166:167], v[166:167], 1.0 op_sel_hi:[1,0]
	v_rcp_f32_e32 v128, v128
	v_rcp_f32_e32 v129, v129
	v_rcp_f32_e32 v130, v130
	v_rcp_f32_e32 v131, v131
	v_rcp_f32_e32 v132, v132
	v_rcp_f32_e32 v133, v133
	v_rcp_f32_e32 v134, v134
	v_rcp_f32_e32 v135, v135
	v_rcp_f32_e32 v160, v160
	v_rcp_f32_e32 v161, v161
	v_rcp_f32_e32 v162, v162
	v_rcp_f32_e32 v163, v163
	v_rcp_f32_e32 v164, v164
	v_rcp_f32_e32 v165, v165
	v_rcp_f32_e32 v166, v166
	v_rcp_f32_e32 v167, v167
	v_max_f32_e32 v128, s25, v128
	v_max_f32_e32 v129, s25, v129
	v_max_f32_e32 v130, s25, v130
	v_max_f32_e32 v131, s25, v131
	v_max_f32_e32 v132, s25, v132
	v_max_f32_e32 v133, s25, v133
	v_max_f32_e32 v134, s25, v134
	v_max_f32_e32 v135, s25, v135
	v_max_f32_e32 v160, s25, v160
	v_max_f32_e32 v161, s25, v161
	v_max_f32_e32 v162, s25, v162
	v_max_f32_e32 v163, s25, v163
	v_max_f32_e32 v164, s25, v164
	v_max_f32_e32 v165, s25, v165
	v_max_f32_e32 v166, s25, v166
	v_max_f32_e32 v167, s25, v167
	v_cvt_pk_bf16_f32 v128, v128, v129
	v_cvt_pk_bf16_f32 v129, v130, v131
	v_cvt_pk_bf16_f32 v130, v132, v133
	v_cvt_pk_bf16_f32 v131, v134, v135
	v_cvt_pk_bf16_f32 v160, v160, v161
	global_store_dwordx4 v[170:171], v[128:131], off
	v_cvt_pk_bf16_f32 v161, v162, v163
	v_cvt_pk_bf16_f32 v162, v164, v165
	v_cvt_pk_bf16_f32 v163, v166, v167
	s_nop 0
	global_store_dwordx4 v[170:171], v[160:163], off offset:256
	s_mov_b64 s[34:35], 0x48000
	v_pk_mul_f32 v[128:129], v[44:45], s[24:25] op_sel_hi:[1,0]
	v_pk_mul_f32 v[130:131], v[46:47], s[24:25] op_sel_hi:[1,0]
	v_pk_mul_f32 v[132:133], v[40:41], s[24:25] op_sel_hi:[1,0]
	v_pk_mul_f32 v[134:135], v[42:43], s[24:25] op_sel_hi:[1,0]
	v_pk_mul_f32 v[160:161], v[36:37], s[24:25] op_sel_hi:[1,0]
	v_pk_mul_f32 v[162:163], v[38:39], s[24:25] op_sel_hi:[1,0]
	v_pk_mul_f32 v[164:165], v[32:33], s[24:25] op_sel_hi:[1,0]
	v_pk_mul_f32 v[166:167], v[34:35], s[24:25] op_sel_hi:[1,0]
	v_exp_f32_e32 v128, v128
	v_exp_f32_e32 v129, v129
	v_exp_f32_e32 v130, v130
	v_exp_f32_e32 v131, v131
	v_exp_f32_e32 v132, v132
	v_exp_f32_e32 v133, v133
	v_exp_f32_e32 v134, v134
	v_exp_f32_e32 v135, v135
	v_exp_f32_e32 v160, v160
	v_exp_f32_e32 v161, v161
	v_exp_f32_e32 v162, v162
	v_exp_f32_e32 v163, v163
	v_exp_f32_e32 v164, v164
	v_exp_f32_e32 v165, v165
	v_exp_f32_e32 v166, v166
	v_exp_f32_e32 v167, v167
	v_lshl_add_u64 v[168:169], v[158:159], 0, s[34:35]
	v_pk_add_f32 v[128:129], v[128:129], 1.0 op_sel_hi:[1,0]
	v_pk_add_f32 v[130:131], v[130:131], 1.0 op_sel_hi:[1,0]
	v_pk_add_f32 v[132:133], v[132:133], 1.0 op_sel_hi:[1,0]
	v_pk_add_f32 v[134:135], v[134:135], 1.0 op_sel_hi:[1,0]
	v_pk_add_f32 v[160:161], v[160:161], 1.0 op_sel_hi:[1,0]
	v_pk_add_f32 v[162:163], v[162:163], 1.0 op_sel_hi:[1,0]
	v_pk_add_f32 v[164:165], v[164:165], 1.0 op_sel_hi:[1,0]
	v_pk_add_f32 v[166:167], v[166:167], 1.0 op_sel_hi:[1,0]
	v_rcp_f32_e32 v128, v128
	v_rcp_f32_e32 v129, v129
	v_rcp_f32_e32 v130, v130
	v_rcp_f32_e32 v131, v131
	v_rcp_f32_e32 v132, v132
	v_rcp_f32_e32 v133, v133
	v_rcp_f32_e32 v134, v134
	v_rcp_f32_e32 v135, v135
	v_rcp_f32_e32 v160, v160
	v_rcp_f32_e32 v161, v161
	v_rcp_f32_e32 v162, v162
	v_rcp_f32_e32 v163, v163
	v_rcp_f32_e32 v164, v164
	v_rcp_f32_e32 v165, v165
	v_rcp_f32_e32 v166, v166
	v_rcp_f32_e32 v167, v167
	v_max_f32_e32 v128, s25, v128
	v_max_f32_e32 v129, s25, v129
	v_max_f32_e32 v130, s25, v130
	v_max_f32_e32 v131, s25, v131
	v_max_f32_e32 v132, s25, v132
	v_max_f32_e32 v133, s25, v133
	v_max_f32_e32 v134, s25, v134
	v_max_f32_e32 v135, s25, v135
	v_max_f32_e32 v160, s25, v160
	v_max_f32_e32 v161, s25, v161
	v_max_f32_e32 v162, s25, v162
	v_max_f32_e32 v163, s25, v163
	v_max_f32_e32 v164, s25, v164
	v_max_f32_e32 v165, s25, v165
	v_max_f32_e32 v166, s25, v166
	v_max_f32_e32 v167, s25, v167
	v_cvt_pk_bf16_f32 v128, v128, v129
	v_cvt_pk_bf16_f32 v129, v130, v131
	v_cvt_pk_bf16_f32 v130, v132, v133
	v_cvt_pk_bf16_f32 v131, v134, v135
	v_cvt_pk_bf16_f32 v160, v160, v161
	global_store_dwordx4 v[168:169], v[128:131], off
	v_cvt_pk_bf16_f32 v161, v162, v163
; #define GAS __attribute__((address_space(1)))
; __device__ __forceinline__ float fexp2(float x) { return __builtin_amdgcn_exp2f(x); }
; __device__ __forceinline__ float frcp(float x) { return __builtin_amdgcn_rcpf(x); }
; #define EPI_FOR_ROWS for (int ai = 0; ai < 2; ++ai) _Pragma("unroll") for (int m = 0; m < 4; ++m)
; __device__ __forceinline__ v4u pack8(const f32x4 a, const f32x4 b) { v4u w; w.x = cvt_pk_bf16(a[0], a[1]); w.y = cvt_pk_bf16(a[2], a[3]); w.z = cvt_pk_bf16(b[0], b[1]); w.w = cvt_pk_bf16(b[2], b[3]); return w; }
; #define NT_ST(p, v) __builtin_nontemporal_store((v), (p))
; __device__ __forceinline__ float fsigmoid(float x) { return frcp(1.0f + fexp2(-x * LOG2E)); }
;     __device__ __forceinline__ void operator()(Acc& acc, const Unit& u, int wr, int wc, int fr, int fq, LAS unsigned char* lds) const {
;     ...
;         GAS bf16* dst = (GAS bf16*)(ws + off);
; #pragma unroll
;         EPI_FOR_ROWS { const int row = row0 + ai * 128 + m * 16;
; #pragma unroll
;             for (int bj = 0; bj < 2; ++bj) { f32x4 a = acc[ai][bj][m][0], b = acc[ai][bj][m][1];
;                 if (act) {
; #pragma unroll
;                     for (int j = 0; j < 4; ++j) { const float sa = fsigmoid(a[j]), sb = fsigmoid(b[j]);
;                         a[j] = act == 1 ? a[j] * sa : fmaxf(sa, 1e-30f); b[j] = act == 1 ? b[j] * sb : fmaxf(sb, 1e-30f); } }
;                 NT_ST((GAS v4u*)(dst + (size_t)row * 1024 + cg0 + bj * 128), pack8(a, b)); } }
	v_cvt_pk_bf16_f32 v162, v164, v165
	v_cvt_pk_bf16_f32 v163, v166, v167
	s_nop 0
	global_store_dwordx4 v[168:169], v[160:163], off offset:256
	s_mov_b64 s[34:35], 0x50000
	v_pk_mul_f32 v[128:129], v[28:29], s[24:25] op_sel_hi:[1,0]
	v_pk_mul_f32 v[130:131], v[30:31], s[24:25] op_sel_hi:[1,0]
	v_pk_mul_f32 v[132:133], v[24:25], s[24:25] op_sel_hi:[1,0]
	v_pk_mul_f32 v[134:135], v[26:27], s[24:25] op_sel_hi:[1,0]
	v_pk_mul_f32 v[160:161], v[20:21], s[24:25] op_sel_hi:[1,0]
	v_pk_mul_f32 v[162:163], v[22:23], s[24:25] op_sel_hi:[1,0]
	v_pk_mul_f32 v[164:165], v[16:17], s[24:25] op_sel_hi:[1,0]
	v_pk_mul_f32 v[166:167], v[18:19], s[24:25] op_sel_hi:[1,0]
	v_exp_f32_e32 v128, v128
	v_exp_f32_e32 v129, v129
	v_exp_f32_e32 v130, v130
	v_exp_f32_e32 v131, v131
	v_exp_f32_e32 v132, v132
	v_exp_f32_e32 v133, v133
	v_exp_f32_e32 v134, v134
	v_exp_f32_e32 v135, v135
	v_exp_f32_e32 v160, v160
	v_exp_f32_e32 v161, v161
	v_exp_f32_e32 v162, v162
	v_exp_f32_e32 v163, v163
	v_exp_f32_e32 v164, v164
	v_exp_f32_e32 v165, v165
	v_exp_f32_e32 v166, v166
	v_exp_f32_e32 v167, v167
	v_lshl_add_u64 v[170:171], v[158:159], 0, s[34:35]
	v_pk_add_f32 v[128:129], v[128:129], 1.0 op_sel_hi:[1,0]
	v_pk_add_f32 v[130:131], v[130:131], 1.0 op_sel_hi:[1,0]
	v_pk_add_f32 v[132:133], v[132:133], 1.0 op_sel_hi:[1,0]
	v_pk_add_f32 v[134:135], v[134:135], 1.0 op_sel_hi:[1,0]
	v_pk_add_f32 v[160:161], v[160:161], 1.0 op_sel_hi:[1,0]
	v_pk_add_f32 v[162:163], v[162:163], 1.0 op_sel_hi:[1,0]
	v_pk_add_f32 v[164:165], v[164:165], 1.0 op_sel_hi:[1,0]
	v_pk_add_f32 v[166:167], v[166:167], 1.0 op_sel_hi:[1,0]
	v_rcp_f32_e32 v128, v128
	v_rcp_f32_e32 v129, v129
	v_rcp_f32_e32 v130, v130
	v_rcp_f32_e32 v131, v131
	v_rcp_f32_e32 v132, v132
	v_rcp_f32_e32 v133, v133
	v_rcp_f32_e32 v134, v134
	v_rcp_f32_e32 v135, v135
	v_rcp_f32_e32 v160, v160
	v_rcp_f32_e32 v161, v161
	v_rcp_f32_e32 v162, v162
	v_rcp_f32_e32 v163, v163
	v_rcp_f32_e32 v164, v164
	v_rcp_f32_e32 v165, v165
	v_rcp_f32_e32 v166, v166
	v_rcp_f32_e32 v167, v167
	v_max_f32_e32 v128, s25, v128
	v_max_f32_e32 v129, s25, v129
	v_max_f32_e32 v130, s25, v130
	v_max_f32_e32 v131, s25, v131
	v_max_f32_e32 v132, s25, v132
	v_max_f32_e32 v133, s25, v133
	v_max_f32_e32 v134, s25, v134
	v_max_f32_e32 v135, s25, v135
	v_max_f32_e32 v160, s25, v160
	v_max_f32_e32 v161, s25, v161
	v_max_f32_e32 v162, s25, v162
	v_max_f32_e32 v163, s25, v163
	v_max_f32_e32 v164, s25, v164
	v_max_f32_e32 v165, s25, v165
	v_max_f32_e32 v166, s25, v166
	v_max_f32_e32 v167, s25, v167
	v_cvt_pk_bf16_f32 v128, v128, v129
	v_cvt_pk_bf16_f32 v129, v130, v131
	v_cvt_pk_bf16_f32 v130, v132, v133
	v_cvt_pk_bf16_f32 v131, v134, v135
	v_cvt_pk_bf16_f32 v160, v160, v161
	global_store_dwordx4 v[170:171], v[128:131], off
	v_cvt_pk_bf16_f32 v161, v162, v163
	v_cvt_pk_bf16_f32 v162, v164, v165
	v_cvt_pk_bf16_f32 v163, v166, v167
	s_nop 0
	global_store_dwordx4 v[170:171], v[160:163], off offset:256
	s_mov_b64 s[34:35], 0x58000
	v_pk_mul_f32 v[128:129], v[12:13], s[24:25] op_sel_hi:[1,0]
	v_pk_mul_f32 v[130:131], v[14:15], s[24:25] op_sel_hi:[1,0]
	v_pk_mul_f32 v[132:133], v[8:9], s[24:25] op_sel_hi:[1,0]
	v_pk_mul_f32 v[134:135], v[10:11], s[24:25] op_sel_hi:[1,0]
	v_pk_mul_f32 v[160:161], v[4:5], s[24:25] op_sel_hi:[1,0]
	v_pk_mul_f32 v[162:163], v[6:7], s[24:25] op_sel_hi:[1,0]
	v_pk_mul_f32 v[164:165], v[0:1], s[24:25] op_sel_hi:[1,0]
	v_pk_mul_f32 v[166:167], v[2:3], s[24:25] op_sel_hi:[1,0]
	v_exp_f32_e32 v128, v128
	v_exp_f32_e32 v129, v129
	v_exp_f32_e32 v130, v130
	v_exp_f32_e32 v131, v131
	v_exp_f32_e32 v132, v132
	v_exp_f32_e32 v133, v133
	v_exp_f32_e32 v134, v134
	v_exp_f32_e32 v135, v135
	v_exp_f32_e32 v160, v160
	v_exp_f32_e32 v161, v161
	v_exp_f32_e32 v162, v162
	v_exp_f32_e32 v163, v163
	v_exp_f32_e32 v164, v164
	v_exp_f32_e32 v165, v165
	v_exp_f32_e32 v166, v166
	v_exp_f32_e32 v167, v167
	v_lshl_add_u64 v[168:169], v[158:159], 0, s[34:35]
	v_pk_add_f32 v[128:129], v[128:129], 1.0 op_sel_hi:[1,0]
	v_pk_add_f32 v[130:131], v[130:131], 1.0 op_sel_hi:[1,0]
	v_pk_add_f32 v[132:133], v[132:133], 1.0 op_sel_hi:[1,0]
	v_pk_add_f32 v[134:135], v[134:135], 1.0 op_sel_hi:[1,0]
	v_pk_add_f32 v[160:161], v[160:161], 1.0 op_sel_hi:[1,0]
	v_pk_add_f32 v[162:163], v[162:163], 1.0 op_sel_hi:[1,0]
	v_pk_add_f32 v[164:165], v[164:165], 1.0 op_sel_hi:[1,0]
	v_pk_add_f32 v[166:167], v[166:167], 1.0 op_sel_hi:[1,0]
	v_rcp_f32_e32 v128, v128
	v_rcp_f32_e32 v129, v129
	v_rcp_f32_e32 v130, v130
	v_rcp_f32_e32 v131, v131
	v_rcp_f32_e32 v132, v132
	v_rcp_f32_e32 v133, v133
	v_rcp_f32_e32 v134, v134
	v_rcp_f32_e32 v135, v135
	v_rcp_f32_e32 v160, v160
	v_rcp_f32_e32 v161, v161
	v_rcp_f32_e32 v162, v162
	v_rcp_f32_e32 v163, v163
	v_rcp_f32_e32 v164, v164
	v_rcp_f32_e32 v165, v165
	v_rcp_f32_e32 v166, v166
	v_rcp_f32_e32 v167, v167
	v_max_f32_e32 v128, s25, v128
	v_max_f32_e32 v129, s25, v129
	v_max_f32_e32 v130, s25, v130
	v_max_f32_e32 v131, s25, v131
	v_max_f32_e32 v132, s25, v132
	v_max_f32_e32 v133, s25, v133
	v_max_f32_e32 v134, s25, v134
	v_max_f32_e32 v135, s25, v135
	v_max_f32_e32 v160, s25, v160
	v_max_f32_e32 v161, s25, v161
	v_max_f32_e32 v162, s25, v162
	v_max_f32_e32 v163, s25, v163
	v_max_f32_e32 v164, s25, v164
	v_max_f32_e32 v165, s25, v165
	v_max_f32_e32 v166, s25, v166
	v_max_f32_e32 v167, s25, v167
	v_cvt_pk_bf16_f32 v128, v128, v129
	v_cvt_pk_bf16_f32 v129, v130, v131
	v_cvt_pk_bf16_f32 v130, v132, v133
	v_cvt_pk_bf16_f32 v131, v134, v135
	v_cvt_pk_bf16_f32 v160, v160, v161
	global_store_dwordx4 v[168:169], v[128:131], off
	v_cvt_pk_bf16_f32 v161, v162, v163
	v_cvt_pk_bf16_f32 v162, v164, v165
	v_cvt_pk_bf16_f32 v163, v166, v167
	s_nop 0
	global_store_dwordx4 v[168:169], v[160:163], off offset:256
	s_branch .Lep_done
; #define GAS __attribute__((address_space(1)))
; __device__ __forceinline__ float fexp2(float x) { return __builtin_amdgcn_exp2f(x); }
; __device__ __forceinline__ float frcp(float x) { return __builtin_amdgcn_rcpf(x); }
; #define EPI_FOR_ROWS for (int ai = 0; ai < 2; ++ai) _Pragma("unroll") for (int m = 0; m < 4; ++m)
; __device__ __forceinline__ v4u pack8(const f32x4 a, const f32x4 b) { v4u w; w.x = cvt_pk_bf16(a[0], a[1]); w.y = cvt_pk_bf16(a[2], a[3]); w.z = cvt_pk_bf16(b[0], b[1]); w.w = cvt_pk_bf16(b[2], b[3]); return w; }
; #define NT_ST(p, v) __builtin_nontemporal_store((v), (p))
; __device__ __forceinline__ float fsigmoid(float x) { return frcp(1.0f + fexp2(-x * LOG2E)); }
; __device__ __forceinline__ float fsilu(float x) { return x * fsigmoid(x); }
;     __device__ __forceinline__ void operator()(Acc& acc, const Unit& u, int wr, int wc, int fr, int fq, LAS unsigned char* lds) const {
;     ...
;         EPI_FOR_ROWS { const int row = row0 + ai * 128 + m * 16;
; #pragma unroll
;             for (int bj = 0; bj < 2; ++bj) { f32x4 a = acc[ai][bj][m][0], b = acc[ai][bj][m][1];
;                 if (act) {
; #pragma unroll
;                     for (int j = 0; j < 4; ++j) { const float sa = fsigmoid(a[j]), sb = fsigmoid(b[j]);
;                         a[j] = act == 1 ? a[j] * sa : fmaxf(sa, 1e-30f); b[j] = act == 1 ? b[j] * sb : fmaxf(sb, 1e-30f); } }
;                 NT_ST((GAS v4u*)(dst + (size_t)row * 1024 + cg0 + bj * 128), pack8(a, b)); } }
.Lep_silu:
	v_pk_mul_f32 v[128:129], v[124:125], s[24:25] op_sel_hi:[1,0]
	v_pk_mul_f32 v[130:131], v[126:127], s[24:25] op_sel_hi:[1,0]
	v_pk_mul_f32 v[132:133], v[120:121], s[24:25] op_sel_hi:[1,0]
	v_pk_mul_f32 v[134:135], v[122:123], s[24:25] op_sel_hi:[1,0]
	v_pk_mul_f32 v[160:161], v[116:117], s[24:25] op_sel_hi:[1,0]
	v_pk_mul_f32 v[162:163], v[118:119], s[24:25] op_sel_hi:[1,0]
	v_pk_mul_f32 v[164:165], v[112:113], s[24:25] op_sel_hi:[1,0]
	v_pk_mul_f32 v[166:167], v[114:115], s[24:25] op_sel_hi:[1,0]
	v_exp_f32_e32 v128, v128
	v_exp_f32_e32 v129, v129
	v_exp_f32_e32 v130, v130
	v_exp_f32_e32 v131, v131
	v_exp_f32_e32 v132, v132
	v_exp_f32_e32 v133, v133
	v_exp_f32_e32 v134, v134
	v_exp_f32_e32 v135, v135
	v_exp_f32_e32 v160, v160
	v_exp_f32_e32 v161, v161
	v_exp_f32_e32 v162, v162
	v_exp_f32_e32 v163, v163
	v_exp_f32_e32 v164, v164
	v_exp_f32_e32 v165, v165
	v_exp_f32_e32 v166, v166
	v_exp_f32_e32 v167, v167
	v_pk_add_f32 v[128:129], v[128:129], 1.0 op_sel_hi:[1,0]
	v_pk_add_f32 v[130:131], v[130:131], 1.0 op_sel_hi:[1,0]
	v_pk_add_f32 v[132:133], v[132:133], 1.0 op_sel_hi:[1,0]
	v_pk_add_f32 v[134:135], v[134:135], 1.0 op_sel_hi:[1,0]
	v_pk_add_f32 v[160:161], v[160:161], 1.0 op_sel_hi:[1,0]
	v_pk_add_f32 v[162:163], v[162:163], 1.0 op_sel_hi:[1,0]
	v_pk_add_f32 v[164:165], v[164:165], 1.0 op_sel_hi:[1,0]
	v_pk_add_f32 v[166:167], v[166:167], 1.0 op_sel_hi:[1,0]
	v_rcp_f32_e32 v128, v128
	v_rcp_f32_e32 v129, v129
	v_rcp_f32_e32 v130, v130
	v_rcp_f32_e32 v131, v131
	v_rcp_f32_e32 v132, v132
	v_rcp_f32_e32 v133, v133
	v_rcp_f32_e32 v134, v134
	v_rcp_f32_e32 v135, v135
	v_rcp_f32_e32 v160, v160
	v_rcp_f32_e32 v161, v161
	v_rcp_f32_e32 v162, v162
	v_rcp_f32_e32 v163, v163
	v_rcp_f32_e32 v164, v164
	v_rcp_f32_e32 v165, v165
	v_rcp_f32_e32 v166, v166
	v_rcp_f32_e32 v167, v167
	v_pk_mul_f32 v[128:129], v[124:125], v[128:129]
	v_pk_mul_f32 v[130:131], v[126:127], v[130:131]
	v_pk_mul_f32 v[132:133], v[120:121], v[132:133]
	v_pk_mul_f32 v[134:135], v[122:123], v[134:135]
	v_pk_mul_f32 v[160:161], v[116:117], v[160:161]
	v_pk_mul_f32 v[162:163], v[118:119], v[162:163]
	v_pk_mul_f32 v[164:165], v[112:113], v[164:165]
	v_pk_mul_f32 v[166:167], v[114:115], v[166:167]
	v_cvt_pk_bf16_f32 v128, v128, v129
	v_cvt_pk_bf16_f32 v129, v130, v131
	v_cvt_pk_bf16_f32 v130, v132, v133
	v_cvt_pk_bf16_f32 v131, v134, v135
	v_cvt_pk_bf16_f32 v160, v160, v161
	global_store_dwordx4 v[158:159], v[128:131], off
	v_cvt_pk_bf16_f32 v161, v162, v163
	v_cvt_pk_bf16_f32 v162, v164, v165
	v_cvt_pk_bf16_f32 v163, v166, v167
	s_nop 0
	global_store_dwordx4 v[158:159], v[160:163], off offset:256
	s_mov_b64 s[34:35], 0x8000
	v_pk_mul_f32 v[128:129], v[108:109], s[24:25] op_sel_hi:[1,0]
	v_pk_mul_f32 v[130:131], v[110:111], s[24:25] op_sel_hi:[1,0]
	v_pk_mul_f32 v[132:133], v[104:105], s[24:25] op_sel_hi:[1,0]
	v_pk_mul_f32 v[134:135], v[106:107], s[24:25] op_sel_hi:[1,0]
	v_pk_mul_f32 v[160:161], v[100:101], s[24:25] op_sel_hi:[1,0]
	v_pk_mul_f32 v[162:163], v[102:103], s[24:25] op_sel_hi:[1,0]
	v_pk_mul_f32 v[164:165], v[96:97], s[24:25] op_sel_hi:[1,0]
	v_pk_mul_f32 v[166:167], v[98:99], s[24:25] op_sel_hi:[1,0]
	v_exp_f32_e32 v128, v128
	v_exp_f32_e32 v129, v129
	v_exp_f32_e32 v130, v130
	v_exp_f32_e32 v131, v131
	v_exp_f32_e32 v132, v132
	v_exp_f32_e32 v133, v133
	v_exp_f32_e32 v134, v134
	v_exp_f32_e32 v135, v135
	v_exp_f32_e32 v160, v160
	v_exp_f32_e32 v161, v161
	v_exp_f32_e32 v162, v162
	v_exp_f32_e32 v163, v163
	v_exp_f32_e32 v164, v164
	v_exp_f32_e32 v165, v165
	v_exp_f32_e32 v166, v166
	v_exp_f32_e32 v167, v167
	v_lshl_add_u64 v[168:169], v[158:159], 0, s[34:35]
	v_pk_add_f32 v[128:129], v[128:129], 1.0 op_sel_hi:[1,0]
	v_pk_add_f32 v[130:131], v[130:131], 1.0 op_sel_hi:[1,0]
	v_pk_add_f32 v[132:133], v[132:133], 1.0 op_sel_hi:[1,0]
	v_pk_add_f32 v[134:135], v[134:135], 1.0 op_sel_hi:[1,0]
	v_pk_add_f32 v[160:161], v[160:161], 1.0 op_sel_hi:[1,0]
	v_pk_add_f32 v[162:163], v[162:163], 1.0 op_sel_hi:[1,0]
	v_pk_add_f32 v[164:165], v[164:165], 1.0 op_sel_hi:[1,0]
	v_pk_add_f32 v[166:167], v[166:167], 1.0 op_sel_hi:[1,0]
	v_rcp_f32_e32 v128, v128
	v_rcp_f32_e32 v129, v129
	v_rcp_f32_e32 v130, v130
	v_rcp_f32_e32 v131, v131
	v_rcp_f32_e32 v132, v132
	v_rcp_f32_e32 v133, v133
	v_rcp_f32_e32 v134, v134
	v_rcp_f32_e32 v135, v135
	v_rcp_f32_e32 v160, v160
	v_rcp_f32_e32 v161, v161
	v_rcp_f32_e32 v162, v162
	v_rcp_f32_e32 v163, v163
	v_rcp_f32_e32 v164, v164
	v_rcp_f32_e32 v165, v165
	v_rcp_f32_e32 v166, v166
	v_rcp_f32_e32 v167, v167
	v_pk_mul_f32 v[128:129], v[108:109], v[128:129]
	v_pk_mul_f32 v[130:131], v[110:111], v[130:131]
	v_pk_mul_f32 v[132:133], v[104:105], v[132:133]
	v_pk_mul_f32 v[134:135], v[106:107], v[134:135]
	v_pk_mul_f32 v[160:161], v[100:101], v[160:161]
	v_pk_mul_f32 v[162:163], v[102:103], v[162:163]
	v_pk_mul_f32 v[164:165], v[96:97], v[164:165]
	v_pk_mul_f32 v[166:167], v[98:99], v[166:167]
	v_cvt_pk_bf16_f32 v128, v128, v129
	v_cvt_pk_bf16_f32 v129, v130, v131
	v_cvt_pk_bf16_f32 v130, v132, v133
	v_cvt_pk_bf16_f32 v131, v134, v135
	v_cvt_pk_bf16_f32 v160, v160, v161
	global_store_dwordx4 v[168:169], v[128:131], off
	v_cvt_pk_bf16_f32 v161, v162, v163
	v_cvt_pk_bf16_f32 v162, v164, v165
	v_cvt_pk_bf16_f32 v163, v166, v167
	s_nop 0
	global_store_dwordx4 v[168:169], v[160:163], off offset:256
	s_mov_b64 s[34:35], 0x10000
	v_pk_mul_f32 v[128:129], v[92:93], s[24:25] op_sel_hi:[1,0]
	v_pk_mul_f32 v[130:131], v[94:95], s[24:25] op_sel_hi:[1,0]
	v_pk_mul_f32 v[132:133], v[88:89], s[24:25] op_sel_hi:[1,0]
	v_pk_mul_f32 v[134:135], v[90:91], s[24:25] op_sel_hi:[1,0]
	v_pk_mul_f32 v[160:161], v[84:85], s[24:25] op_sel_hi:[1,0]
; #define GAS __attribute__((address_space(1)))
; __device__ __forceinline__ float fexp2(float x) { return __builtin_amdgcn_exp2f(x); }
; __device__ __forceinline__ float frcp(float x) { return __builtin_amdgcn_rcpf(x); }
; #define EPI_FOR_ROWS for (int ai = 0; ai < 2; ++ai) _Pragma("unroll") for (int m = 0; m < 4; ++m)
; __device__ __forceinline__ v4u pack8(const f32x4 a, const f32x4 b) { v4u w; w.x = cvt_pk_bf16(a[0], a[1]); w.y = cvt_pk_bf16(a[2], a[3]); w.z = cvt_pk_bf16(b[0], b[1]); w.w = cvt_pk_bf16(b[2], b[3]); return w; }
; #define NT_ST(p, v) __builtin_nontemporal_store((v), (p))
; __device__ __forceinline__ float fsigmoid(float x) { return frcp(1.0f + fexp2(-x * LOG2E)); }
; __device__ __forceinline__ float fsilu(float x) { return x * fsigmoid(x); }
;     __device__ __forceinline__ void operator()(Acc& acc, const Unit& u, int wr, int wc, int fr, int fq, LAS unsigned char* lds) const {
;     ...
;         EPI_FOR_ROWS { const int row = row0 + ai * 128 + m * 16;
; #pragma unroll
;             for (int bj = 0; bj < 2; ++bj) { f32x4 a = acc[ai][bj][m][0], b = acc[ai][bj][m][1];
;                 if (act) {
; #pragma unroll
;                     for (int j = 0; j < 4; ++j) { const float sa = fsigmoid(a[j]), sb = fsigmoid(b[j]);
;                         a[j] = act == 1 ? a[j] * sa : fmaxf(sa, 1e-30f); b[j] = act == 1 ? b[j] * sb : fmaxf(sb, 1e-30f); } }
;                 NT_ST((GAS v4u*)(dst + (size_t)row * 1024 + cg0 + bj * 128), pack8(a, b)); } }
	v_pk_mul_f32 v[162:163], v[86:87], s[24:25] op_sel_hi:[1,0]
	v_pk_mul_f32 v[164:165], v[80:81], s[24:25] op_sel_hi:[1,0]
	v_pk_mul_f32 v[166:167], v[82:83], s[24:25] op_sel_hi:[1,0]
	v_exp_f32_e32 v128, v128
	v_exp_f32_e32 v129, v129
	v_exp_f32_e32 v130, v130
	v_exp_f32_e32 v131, v131
	v_exp_f32_e32 v132, v132
	v_exp_f32_e32 v133, v133
	v_exp_f32_e32 v134, v134
	v_exp_f32_e32 v135, v135
	v_exp_f32_e32 v160, v160
	v_exp_f32_e32 v161, v161
	v_exp_f32_e32 v162, v162
	v_exp_f32_e32 v163, v163
	v_exp_f32_e32 v164, v164
	v_exp_f32_e32 v165, v165
	v_exp_f32_e32 v166, v166
	v_exp_f32_e32 v167, v167
	v_lshl_add_u64 v[170:171], v[158:159], 0, s[34:35]
	v_pk_add_f32 v[128:129], v[128:129], 1.0 op_sel_hi:[1,0]
	v_pk_add_f32 v[130:131], v[130:131], 1.0 op_sel_hi:[1,0]
	v_pk_add_f32 v[132:133], v[132:133], 1.0 op_sel_hi:[1,0]
	v_pk_add_f32 v[134:135], v[134:135], 1.0 op_sel_hi:[1,0]
	v_pk_add_f32 v[160:161], v[160:161], 1.0 op_sel_hi:[1,0]
	v_pk_add_f32 v[162:163], v[162:163], 1.0 op_sel_hi:[1,0]
	v_pk_add_f32 v[164:165], v[164:165], 1.0 op_sel_hi:[1,0]
	v_pk_add_f32 v[166:167], v[166:167], 1.0 op_sel_hi:[1,0]
	v_rcp_f32_e32 v128, v128
	v_rcp_f32_e32 v129, v129
	v_rcp_f32_e32 v130, v130
	v_rcp_f32_e32 v131, v131
	v_rcp_f32_e32 v132, v132
	v_rcp_f32_e32 v133, v133
	v_rcp_f32_e32 v134, v134
	v_rcp_f32_e32 v135, v135
	v_rcp_f32_e32 v160, v160
	v_rcp_f32_e32 v161, v161
	v_rcp_f32_e32 v162, v162
	v_rcp_f32_e32 v163, v163
	v_rcp_f32_e32 v164, v164
	v_rcp_f32_e32 v165, v165
	v_rcp_f32_e32 v166, v166
	v_rcp_f32_e32 v167, v167
	v_pk_mul_f32 v[128:129], v[92:93], v[128:129]
	v_pk_mul_f32 v[130:131], v[94:95], v[130:131]
	v_pk_mul_f32 v[132:133], v[88:89], v[132:133]
	v_pk_mul_f32 v[134:135], v[90:91], v[134:135]
	v_pk_mul_f32 v[160:161], v[84:85], v[160:161]
	v_pk_mul_f32 v[162:163], v[86:87], v[162:163]
	v_pk_mul_f32 v[164:165], v[80:81], v[164:165]
	v_pk_mul_f32 v[166:167], v[82:83], v[166:167]
	v_cvt_pk_bf16_f32 v128, v128, v129
	v_cvt_pk_bf16_f32 v129, v130, v131
	v_cvt_pk_bf16_f32 v130, v132, v133
	v_cvt_pk_bf16_f32 v131, v134, v135
	v_cvt_pk_bf16_f32 v160, v160, v161
	global_store_dwordx4 v[170:171], v[128:131], off
	v_cvt_pk_bf16_f32 v161, v162, v163
	v_cvt_pk_bf16_f32 v162, v164, v165
	v_cvt_pk_bf16_f32 v163, v166, v167
	s_nop 0
	global_store_dwordx4 v[170:171], v[160:163], off offset:256
	s_mov_b64 s[34:35], 0x18000
	v_pk_mul_f32 v[128:129], v[76:77], s[24:25] op_sel_hi:[1,0]
	v_pk_mul_f32 v[130:131], v[78:79], s[24:25] op_sel_hi:[1,0]
	v_pk_mul_f32 v[132:133], v[72:73], s[24:25] op_sel_hi:[1,0]
	v_pk_mul_f32 v[134:135], v[74:75], s[24:25] op_sel_hi:[1,0]
	v_pk_mul_f32 v[160:161], v[68:69], s[24:25] op_sel_hi:[1,0]
	v_pk_mul_f32 v[162:163], v[70:71], s[24:25] op_sel_hi:[1,0]
	v_pk_mul_f32 v[164:165], v[64:65], s[24:25] op_sel_hi:[1,0]
	v_pk_mul_f32 v[166:167], v[66:67], s[24:25] op_sel_hi:[1,0]
	v_exp_f32_e32 v128, v128
	v_exp_f32_e32 v129, v129
	v_exp_f32_e32 v130, v130
	v_exp_f32_e32 v131, v131
	v_exp_f32_e32 v132, v132
	v_exp_f32_e32 v133, v133
	v_exp_f32_e32 v134, v134
	v_exp_f32_e32 v135, v135
	v_exp_f32_e32 v160, v160
	v_exp_f32_e32 v161, v161
	v_exp_f32_e32 v162, v162
	v_exp_f32_e32 v163, v163
	v_exp_f32_e32 v164, v164
	v_exp_f32_e32 v165, v165
	v_exp_f32_e32 v166, v166
	v_exp_f32_e32 v167, v167
	v_lshl_add_u64 v[168:169], v[158:159], 0, s[34:35]
	v_pk_add_f32 v[128:129], v[128:129], 1.0 op_sel_hi:[1,0]
	v_pk_add_f32 v[130:131], v[130:131], 1.0 op_sel_hi:[1,0]
	v_pk_add_f32 v[132:133], v[132:133], 1.0 op_sel_hi:[1,0]
	v_pk_add_f32 v[134:135], v[134:135], 1.0 op_sel_hi:[1,0]
	v_pk_add_f32 v[160:161], v[160:161], 1.0 op_sel_hi:[1,0]
	v_pk_add_f32 v[162:163], v[162:163], 1.0 op_sel_hi:[1,0]
	v_pk_add_f32 v[164:165], v[164:165], 1.0 op_sel_hi:[1,0]
	v_pk_add_f32 v[166:167], v[166:167], 1.0 op_sel_hi:[1,0]
	v_rcp_f32_e32 v128, v128
	v_rcp_f32_e32 v129, v129
	v_rcp_f32_e32 v130, v130
	v_rcp_f32_e32 v131, v131
	v_rcp_f32_e32 v132, v132
	v_rcp_f32_e32 v133, v133
	v_rcp_f32_e32 v134, v134
	v_rcp_f32_e32 v135, v135
	v_rcp_f32_e32 v160, v160
	v_rcp_f32_e32 v161, v161
	v_rcp_f32_e32 v162, v162
	v_rcp_f32_e32 v163, v163
	v_rcp_f32_e32 v164, v164
	v_rcp_f32_e32 v165, v165
	v_rcp_f32_e32 v166, v166
	v_rcp_f32_e32 v167, v167
	v_pk_mul_f32 v[128:129], v[76:77], v[128:129]
	v_pk_mul_f32 v[130:131], v[78:79], v[130:131]
	v_pk_mul_f32 v[132:133], v[72:73], v[132:133]
	v_pk_mul_f32 v[134:135], v[74:75], v[134:135]
	v_pk_mul_f32 v[160:161], v[68:69], v[160:161]
	v_pk_mul_f32 v[162:163], v[70:71], v[162:163]
	v_pk_mul_f32 v[164:165], v[64:65], v[164:165]
	v_pk_mul_f32 v[166:167], v[66:67], v[166:167]
	v_cvt_pk_bf16_f32 v128, v128, v129
	v_cvt_pk_bf16_f32 v129, v130, v131
	v_cvt_pk_bf16_f32 v130, v132, v133
	v_cvt_pk_bf16_f32 v131, v134, v135
	v_cvt_pk_bf16_f32 v160, v160, v161
	global_store_dwordx4 v[168:169], v[128:131], off
	v_cvt_pk_bf16_f32 v161, v162, v163
	v_cvt_pk_bf16_f32 v162, v164, v165
	v_cvt_pk_bf16_f32 v163, v166, v167
	s_nop 0
	global_store_dwordx4 v[168:169], v[160:163], off offset:256
	s_mov_b64 s[34:35], 0x40000
	v_pk_mul_f32 v[128:129], v[60:61], s[24:25] op_sel_hi:[1,0]
	v_pk_mul_f32 v[130:131], v[62:63], s[24:25] op_sel_hi:[1,0]
	v_pk_mul_f32 v[132:133], v[56:57], s[24:25] op_sel_hi:[1,0]
	v_pk_mul_f32 v[134:135], v[58:59], s[24:25] op_sel_hi:[1,0]
	v_pk_mul_f32 v[160:161], v[52:53], s[24:25] op_sel_hi:[1,0]
	v_pk_mul_f32 v[162:163], v[54:55], s[24:25] op_sel_hi:[1,0]
	v_pk_mul_f32 v[164:165], v[48:49], s[24:25] op_sel_hi:[1,0]
	v_pk_mul_f32 v[166:167], v[50:51], s[24:25] op_sel_hi:[1,0]
	v_exp_f32_e32 v128, v128
	v_exp_f32_e32 v129, v129
	v_exp_f32_e32 v130, v130
	v_exp_f32_e32 v131, v131
	v_exp_f32_e32 v132, v132
	v_exp_f32_e32 v133, v133
; #define GAS __attribute__((address_space(1)))
; __device__ __forceinline__ float fexp2(float x) { return __builtin_amdgcn_exp2f(x); }
; __device__ __forceinline__ float frcp(float x) { return __builtin_amdgcn_rcpf(x); }
; #define EPI_FOR_ROWS for (int ai = 0; ai < 2; ++ai) _Pragma("unroll") for (int m = 0; m < 4; ++m)
; __device__ __forceinline__ v4u pack8(const f32x4 a, const f32x4 b) { v4u w; w.x = cvt_pk_bf16(a[0], a[1]); w.y = cvt_pk_bf16(a[2], a[3]); w.z = cvt_pk_bf16(b[0], b[1]); w.w = cvt_pk_bf16(b[2], b[3]); return w; }
; #define NT_ST(p, v) __builtin_nontemporal_store((v), (p))
; __device__ __forceinline__ float fsigmoid(float x) { return frcp(1.0f + fexp2(-x * LOG2E)); }
; __device__ __forceinline__ float fsilu(float x) { return x * fsigmoid(x); }
;     __device__ __forceinline__ void operator()(Acc& acc, const Unit& u, int wr, int wc, int fr, int fq, LAS unsigned char* lds) const {
;     ...
;         EPI_FOR_ROWS { const int row = row0 + ai * 128 + m * 16;
; #pragma unroll
;             for (int bj = 0; bj < 2; ++bj) { f32x4 a = acc[ai][bj][m][0], b = acc[ai][bj][m][1];
;                 if (act) {
; #pragma unroll
;                     for (int j = 0; j < 4; ++j) { const float sa = fsigmoid(a[j]), sb = fsigmoid(b[j]);
;                         a[j] = act == 1 ? a[j] * sa : fmaxf(sa, 1e-30f); b[j] = act == 1 ? b[j] * sb : fmaxf(sb, 1e-30f); } }
;                 NT_ST((GAS v4u*)(dst + (size_t)row * 1024 + cg0 + bj * 128), pack8(a, b)); } }
	v_exp_f32_e32 v134, v134
	v_exp_f32_e32 v135, v135
	v_exp_f32_e32 v160, v160
	v_exp_f32_e32 v161, v161
	v_exp_f32_e32 v162, v162
	v_exp_f32_e32 v163, v163
	v_exp_f32_e32 v164, v164
	v_exp_f32_e32 v165, v165
	v_exp_f32_e32 v166, v166
	v_exp_f32_e32 v167, v167
	v_lshl_add_u64 v[170:171], v[158:159], 0, s[34:35]
	v_pk_add_f32 v[128:129], v[128:129], 1.0 op_sel_hi:[1,0]
	v_pk_add_f32 v[130:131], v[130:131], 1.0 op_sel_hi:[1,0]
	v_pk_add_f32 v[132:133], v[132:133], 1.0 op_sel_hi:[1,0]
	v_pk_add_f32 v[134:135], v[134:135], 1.0 op_sel_hi:[1,0]
	v_pk_add_f32 v[160:161], v[160:161], 1.0 op_sel_hi:[1,0]
	v_pk_add_f32 v[162:163], v[162:163], 1.0 op_sel_hi:[1,0]
	v_pk_add_f32 v[164:165], v[164:165], 1.0 op_sel_hi:[1,0]
	v_pk_add_f32 v[166:167], v[166:167], 1.0 op_sel_hi:[1,0]
	v_rcp_f32_e32 v128, v128
	v_rcp_f32_e32 v129, v129
	v_rcp_f32_e32 v130, v130
	v_rcp_f32_e32 v131, v131
	v_rcp_f32_e32 v132, v132
	v_rcp_f32_e32 v133, v133
	v_rcp_f32_e32 v134, v134
	v_rcp_f32_e32 v135, v135
	v_rcp_f32_e32 v160, v160
	v_rcp_f32_e32 v161, v161
	v_rcp_f32_e32 v162, v162
	v_rcp_f32_e32 v163, v163
	v_rcp_f32_e32 v164, v164
	v_rcp_f32_e32 v165, v165
	v_rcp_f32_e32 v166, v166
	v_rcp_f32_e32 v167, v167
	v_pk_mul_f32 v[128:129], v[60:61], v[128:129]
	v_pk_mul_f32 v[130:131], v[62:63], v[130:131]
	v_pk_mul_f32 v[132:133], v[56:57], v[132:133]
	v_pk_mul_f32 v[134:135], v[58:59], v[134:135]
	v_pk_mul_f32 v[160:161], v[52:53], v[160:161]
	v_pk_mul_f32 v[162:163], v[54:55], v[162:163]
	v_pk_mul_f32 v[164:165], v[48:49], v[164:165]
	v_pk_mul_f32 v[166:167], v[50:51], v[166:167]
	v_cvt_pk_bf16_f32 v128, v128, v129
	v_cvt_pk_bf16_f32 v129, v130, v131
	v_cvt_pk_bf16_f32 v130, v132, v133
	v_cvt_pk_bf16_f32 v131, v134, v135
	v_cvt_pk_bf16_f32 v160, v160, v161
	global_store_dwordx4 v[170:171], v[128:131], off
	v_cvt_pk_bf16_f32 v161, v162, v163
	v_cvt_pk_bf16_f32 v162, v164, v165
	v_cvt_pk_bf16_f32 v163, v166, v167
	s_nop 0
	global_store_dwordx4 v[170:171], v[160:163], off offset:256
	s_mov_b64 s[34:35], 0x48000
	v_pk_mul_f32 v[128:129], v[44:45], s[24:25] op_sel_hi:[1,0]
	v_pk_mul_f32 v[130:131], v[46:47], s[24:25] op_sel_hi:[1,0]
	v_pk_mul_f32 v[132:133], v[40:41], s[24:25] op_sel_hi:[1,0]
	v_pk_mul_f32 v[134:135], v[42:43], s[24:25] op_sel_hi:[1,0]
	v_pk_mul_f32 v[160:161], v[36:37], s[24:25] op_sel_hi:[1,0]
	v_pk_mul_f32 v[162:163], v[38:39], s[24:25] op_sel_hi:[1,0]
	v_pk_mul_f32 v[164:165], v[32:33], s[24:25] op_sel_hi:[1,0]
	v_pk_mul_f32 v[166:167], v[34:35], s[24:25] op_sel_hi:[1,0]
	v_exp_f32_e32 v128, v128
	v_exp_f32_e32 v129, v129
	v_exp_f32_e32 v130, v130
	v_exp_f32_e32 v131, v131
	v_exp_f32_e32 v132, v132
	v_exp_f32_e32 v133, v133
	v_exp_f32_e32 v134, v134
	v_exp_f32_e32 v135, v135
	v_exp_f32_e32 v160, v160
	v_exp_f32_e32 v161, v161
	v_exp_f32_e32 v162, v162
	v_exp_f32_e32 v163, v163
	v_exp_f32_e32 v164, v164
	v_exp_f32_e32 v165, v165
	v_exp_f32_e32 v166, v166
	v_exp_f32_e32 v167, v167
	v_lshl_add_u64 v[168:169], v[158:159], 0, s[34:35]
	v_pk_add_f32 v[128:129], v[128:129], 1.0 op_sel_hi:[1,0]
	v_pk_add_f32 v[130:131], v[130:131], 1.0 op_sel_hi:[1,0]
	v_pk_add_f32 v[132:133], v[132:133], 1.0 op_sel_hi:[1,0]
	v_pk_add_f32 v[134:135], v[134:135], 1.0 op_sel_hi:[1,0]
	v_pk_add_f32 v[160:161], v[160:161], 1.0 op_sel_hi:[1,0]
	v_pk_add_f32 v[162:163], v[162:163], 1.0 op_sel_hi:[1,0]
	v_pk_add_f32 v[164:165], v[164:165], 1.0 op_sel_hi:[1,0]
	v_pk_add_f32 v[166:167], v[166:167], 1.0 op_sel_hi:[1,0]
	v_rcp_f32_e32 v128, v128
	v_rcp_f32_e32 v129, v129
	v_rcp_f32_e32 v130, v130
	v_rcp_f32_e32 v131, v131
	v_rcp_f32_e32 v132, v132
	v_rcp_f32_e32 v133, v133
	v_rcp_f32_e32 v134, v134
	v_rcp_f32_e32 v135, v135
	v_rcp_f32_e32 v160, v160
	v_rcp_f32_e32 v161, v161
	v_rcp_f32_e32 v162, v162
	v_rcp_f32_e32 v163, v163
	v_rcp_f32_e32 v164, v164
	v_rcp_f32_e32 v165, v165
	v_rcp_f32_e32 v166, v166
	v_rcp_f32_e32 v167, v167
	v_pk_mul_f32 v[128:129], v[44:45], v[128:129]
	v_pk_mul_f32 v[130:131], v[46:47], v[130:131]
	v_pk_mul_f32 v[132:133], v[40:41], v[132:133]
	v_pk_mul_f32 v[134:135], v[42:43], v[134:135]
	v_pk_mul_f32 v[160:161], v[36:37], v[160:161]
	v_pk_mul_f32 v[162:163], v[38:39], v[162:163]
	v_pk_mul_f32 v[164:165], v[32:33], v[164:165]
	v_pk_mul_f32 v[166:167], v[34:35], v[166:167]
	v_cvt_pk_bf16_f32 v128, v128, v129
	v_cvt_pk_bf16_f32 v129, v130, v131
	v_cvt_pk_bf16_f32 v130, v132, v133
	v_cvt_pk_bf16_f32 v131, v134, v135
	v_cvt_pk_bf16_f32 v160, v160, v161
	global_store_dwordx4 v[168:169], v[128:131], off
	v_cvt_pk_bf16_f32 v161, v162, v163
	v_cvt_pk_bf16_f32 v162, v164, v165
	v_cvt_pk_bf16_f32 v163, v166, v167
	s_nop 0
	global_store_dwordx4 v[168:169], v[160:163], off offset:256
	s_mov_b64 s[34:35], 0x50000
	v_pk_mul_f32 v[128:129], v[28:29], s[24:25] op_sel_hi:[1,0]
	v_pk_mul_f32 v[130:131], v[30:31], s[24:25] op_sel_hi:[1,0]
	v_pk_mul_f32 v[132:133], v[24:25], s[24:25] op_sel_hi:[1,0]
	v_pk_mul_f32 v[134:135], v[26:27], s[24:25] op_sel_hi:[1,0]
	v_pk_mul_f32 v[160:161], v[20:21], s[24:25] op_sel_hi:[1,0]
	v_pk_mul_f32 v[162:163], v[22:23], s[24:25] op_sel_hi:[1,0]
	v_pk_mul_f32 v[164:165], v[16:17], s[24:25] op_sel_hi:[1,0]
	v_pk_mul_f32 v[166:167], v[18:19], s[24:25] op_sel_hi:[1,0]
	v_exp_f32_e32 v128, v128
	v_exp_f32_e32 v129, v129
	v_exp_f32_e32 v130, v130
	v_exp_f32_e32 v131, v131
	v_exp_f32_e32 v132, v132
	v_exp_f32_e32 v133, v133
	v_exp_f32_e32 v134, v134
	v_exp_f32_e32 v135, v135
	v_exp_f32_e32 v160, v160
	v_exp_f32_e32 v161, v161
	v_exp_f32_e32 v162, v162
	v_exp_f32_e32 v163, v163
	v_exp_f32_e32 v164, v164
	v_exp_f32_e32 v165, v165
	v_exp_f32_e32 v166, v166
	v_exp_f32_e32 v167, v167
	v_lshl_add_u64 v[170:171], v[158:159], 0, s[34:35]
	v_pk_add_f32 v[128:129], v[128:129], 1.0 op_sel_hi:[1,0]
; #define GAS __attribute__((address_space(1)))
; __device__ __forceinline__ float fexp2(float x) { return __builtin_amdgcn_exp2f(x); }
; __device__ __forceinline__ float frcp(float x) { return __builtin_amdgcn_rcpf(x); }
; #define EPI_FOR_ROWS for (int ai = 0; ai < 2; ++ai) _Pragma("unroll") for (int m = 0; m < 4; ++m)
; __device__ __forceinline__ v4u pack8(const f32x4 a, const f32x4 b) { v4u w; w.x = cvt_pk_bf16(a[0], a[1]); w.y = cvt_pk_bf16(a[2], a[3]); w.z = cvt_pk_bf16(b[0], b[1]); w.w = cvt_pk_bf16(b[2], b[3]); return w; }
; #define NT_ST(p, v) __builtin_nontemporal_store((v), (p))
; __device__ __forceinline__ float fsigmoid(float x) { return frcp(1.0f + fexp2(-x * LOG2E)); }
; __device__ __forceinline__ float fsilu(float x) { return x * fsigmoid(x); }
;     __device__ __forceinline__ void operator()(Acc& acc, const Unit& u, int wr, int wc, int fr, int fq, LAS unsigned char* lds) const {
;     ...
;         EPI_FOR_ROWS { const int row = row0 + ai * 128 + m * 16;
; #pragma unroll
;             for (int bj = 0; bj < 2; ++bj) { f32x4 a = acc[ai][bj][m][0], b = acc[ai][bj][m][1];
;                 if (act) {
; #pragma unroll
;                     for (int j = 0; j < 4; ++j) { const float sa = fsigmoid(a[j]), sb = fsigmoid(b[j]);
;                         a[j] = act == 1 ? a[j] * sa : fmaxf(sa, 1e-30f); b[j] = act == 1 ? b[j] * sb : fmaxf(sb, 1e-30f); } }
;                 NT_ST((GAS v4u*)(dst + (size_t)row * 1024 + cg0 + bj * 128), pack8(a, b)); } }
	v_pk_add_f32 v[130:131], v[130:131], 1.0 op_sel_hi:[1,0]
	v_pk_add_f32 v[132:133], v[132:133], 1.0 op_sel_hi:[1,0]
	v_pk_add_f32 v[134:135], v[134:135], 1.0 op_sel_hi:[1,0]
	v_pk_add_f32 v[160:161], v[160:161], 1.0 op_sel_hi:[1,0]
	v_pk_add_f32 v[162:163], v[162:163], 1.0 op_sel_hi:[1,0]
	v_pk_add_f32 v[164:165], v[164:165], 1.0 op_sel_hi:[1,0]
	v_pk_add_f32 v[166:167], v[166:167], 1.0 op_sel_hi:[1,0]
	v_rcp_f32_e32 v128, v128
	v_rcp_f32_e32 v129, v129
	v_rcp_f32_e32 v130, v130
	v_rcp_f32_e32 v131, v131
	v_rcp_f32_e32 v132, v132
	v_rcp_f32_e32 v133, v133
	v_rcp_f32_e32 v134, v134
	v_rcp_f32_e32 v135, v135
	v_rcp_f32_e32 v160, v160
	v_rcp_f32_e32 v161, v161
	v_rcp_f32_e32 v162, v162
	v_rcp_f32_e32 v163, v163
	v_rcp_f32_e32 v164, v164
	v_rcp_f32_e32 v165, v165
	v_rcp_f32_e32 v166, v166
	v_rcp_f32_e32 v167, v167
	v_pk_mul_f32 v[128:129], v[28:29], v[128:129]
	v_pk_mul_f32 v[130:131], v[30:31], v[130:131]
	v_pk_mul_f32 v[132:133], v[24:25], v[132:133]
	v_pk_mul_f32 v[134:135], v[26:27], v[134:135]
	v_pk_mul_f32 v[160:161], v[20:21], v[160:161]
	v_pk_mul_f32 v[162:163], v[22:23], v[162:163]
	v_pk_mul_f32 v[164:165], v[16:17], v[164:165]
	v_pk_mul_f32 v[166:167], v[18:19], v[166:167]
	v_cvt_pk_bf16_f32 v128, v128, v129
	v_cvt_pk_bf16_f32 v129, v130, v131
	v_cvt_pk_bf16_f32 v130, v132, v133
	v_cvt_pk_bf16_f32 v131, v134, v135
	v_cvt_pk_bf16_f32 v160, v160, v161
	global_store_dwordx4 v[170:171], v[128:131], off
	v_cvt_pk_bf16_f32 v161, v162, v163
	v_cvt_pk_bf16_f32 v162, v164, v165
	v_cvt_pk_bf16_f32 v163, v166, v167
	s_nop 0
	global_store_dwordx4 v[170:171], v[160:163], off offset:256
	s_mov_b64 s[34:35], 0x58000
	v_pk_mul_f32 v[128:129], v[12:13], s[24:25] op_sel_hi:[1,0]
	v_pk_mul_f32 v[130:131], v[14:15], s[24:25] op_sel_hi:[1,0]
	v_pk_mul_f32 v[132:133], v[8:9], s[24:25] op_sel_hi:[1,0]
	v_pk_mul_f32 v[134:135], v[10:11], s[24:25] op_sel_hi:[1,0]
	v_pk_mul_f32 v[160:161], v[4:5], s[24:25] op_sel_hi:[1,0]
	v_pk_mul_f32 v[162:163], v[6:7], s[24:25] op_sel_hi:[1,0]
	v_pk_mul_f32 v[164:165], v[0:1], s[24:25] op_sel_hi:[1,0]
	v_pk_mul_f32 v[166:167], v[2:3], s[24:25] op_sel_hi:[1,0]
	v_exp_f32_e32 v128, v128
	v_exp_f32_e32 v129, v129
	v_exp_f32_e32 v130, v130
	v_exp_f32_e32 v131, v131
	v_exp_f32_e32 v132, v132
	v_exp_f32_e32 v133, v133
	v_exp_f32_e32 v134, v134
	v_exp_f32_e32 v135, v135
	v_exp_f32_e32 v160, v160
	v_exp_f32_e32 v161, v161
	v_exp_f32_e32 v162, v162
	v_exp_f32_e32 v163, v163
	v_exp_f32_e32 v164, v164
	v_exp_f32_e32 v165, v165
	v_exp_f32_e32 v166, v166
	v_exp_f32_e32 v167, v167
	v_lshl_add_u64 v[168:169], v[158:159], 0, s[34:35]
	v_pk_add_f32 v[128:129], v[128:129], 1.0 op_sel_hi:[1,0]
	v_pk_add_f32 v[130:131], v[130:131], 1.0 op_sel_hi:[1,0]
	v_pk_add_f32 v[132:133], v[132:133], 1.0 op_sel_hi:[1,0]
	v_pk_add_f32 v[134:135], v[134:135], 1.0 op_sel_hi:[1,0]
	v_pk_add_f32 v[160:161], v[160:161], 1.0 op_sel_hi:[1,0]
	v_pk_add_f32 v[162:163], v[162:163], 1.0 op_sel_hi:[1,0]
	v_pk_add_f32 v[164:165], v[164:165], 1.0 op_sel_hi:[1,0]
	v_pk_add_f32 v[166:167], v[166:167], 1.0 op_sel_hi:[1,0]
	v_rcp_f32_e32 v128, v128
	v_rcp_f32_e32 v129, v129
	v_rcp_f32_e32 v130, v130
	v_rcp_f32_e32 v131, v131
	v_rcp_f32_e32 v132, v132
	v_rcp_f32_e32 v133, v133
	v_rcp_f32_e32 v134, v134
	v_rcp_f32_e32 v135, v135
	v_rcp_f32_e32 v160, v160
	v_rcp_f32_e32 v161, v161
	v_rcp_f32_e32 v162, v162
	v_rcp_f32_e32 v163, v163
	v_rcp_f32_e32 v164, v164
	v_rcp_f32_e32 v165, v165
	v_rcp_f32_e32 v166, v166
	v_rcp_f32_e32 v167, v167
	v_pk_mul_f32 v[128:129], v[12:13], v[128:129]
	v_pk_mul_f32 v[130:131], v[14:15], v[130:131]
	v_pk_mul_f32 v[132:133], v[8:9], v[132:133]
	v_pk_mul_f32 v[134:135], v[10:11], v[134:135]
	v_pk_mul_f32 v[160:161], v[4:5], v[160:161]
	v_pk_mul_f32 v[162:163], v[6:7], v[162:163]
	v_pk_mul_f32 v[164:165], v[0:1], v[164:165]
	v_pk_mul_f32 v[166:167], v[2:3], v[166:167]
	v_cvt_pk_bf16_f32 v128, v128, v129
	v_cvt_pk_bf16_f32 v129, v130, v131
	v_cvt_pk_bf16_f32 v130, v132, v133
	v_cvt_pk_bf16_f32 v131, v134, v135
	v_cvt_pk_bf16_f32 v160, v160, v161
	global_store_dwordx4 v[168:169], v[128:131], off
	v_cvt_pk_bf16_f32 v161, v162, v163
	v_cvt_pk_bf16_f32 v162, v164, v165
	v_cvt_pk_bf16_f32 v163, v166, v167
	s_nop 0
	global_store_dwordx4 v[168:169], v[160:163], off offset:256
	s_branch .Lep_done
; #define GAS __attribute__((address_space(1)))
; __device__ __forceinline__ float fsigmoid(float x) { return frcp(1.0f + fexp2(-x * LOG2E)); }
; #define EPI_FOR_ROWS for (int ai = 0; ai < 2; ++ai) _Pragma("unroll") for (int m = 0; m < 4; ++m)
; __device__ __forceinline__ v4u pack8(const f32x4 a, const f32x4 b) { v4u w; w.x = cvt_pk_bf16(a[0], a[1]); w.y = cvt_pk_bf16(a[2], a[3]); w.z = cvt_pk_bf16(b[0], b[1]); w.w = cvt_pk_bf16(b[2], b[3]); return w; }
; #define NT_ST(p, v) __builtin_nontemporal_store((v), (p))
;     __device__ __forceinline__ void operator()(Acc& acc, const Unit& u, int wr, int wc, int fr, int fq, LAS unsigned char* lds) const {
;     ...
;         GAS bf16* dst = (GAS bf16*)(ws + off);
; #pragma unroll
;         EPI_FOR_ROWS { const int row = row0 + ai * 128 + m * 16;
; #pragma unroll
;             for (int bj = 0; bj < 2; ++bj) { f32x4 a = acc[ai][bj][m][0], b = acc[ai][bj][m][1];
;                 if (act) {
; #pragma unroll
;                     for (int j = 0; j < 4; ++j) { const float sa = fsigmoid(a[j]), sb = fsigmoid(b[j]);
;                         a[j] = act == 1 ? a[j] * sa : fmaxf(sa, 1e-30f); b[j] = act == 1 ? b[j] * sb : fmaxf(sb, 1e-30f); } }
;                 NT_ST((GAS v4u*)(dst + (size_t)row * 1024 + cg0 + bj * 128), pack8(a, b)); } }
.Lep_none:
	v_cvt_pk_bf16_f32 v128, v124, v125
	v_cvt_pk_bf16_f32 v129, v126, v127
	v_cvt_pk_bf16_f32 v130, v120, v121
	v_cvt_pk_bf16_f32 v131, v122, v123
	v_cvt_pk_bf16_f32 v160, v116, v117
	v_cvt_pk_bf16_f32 v161, v118, v119
	v_cvt_pk_bf16_f32 v162, v112, v113
	v_cvt_pk_bf16_f32 v163, v114, v115
	s_nop 0
	global_store_dwordx4 v[158:159], v[128:131], off
	global_store_dwordx4 v[158:159], v[160:163], off offset:256
	s_mov_b64 s[34:35], 0x8000
	v_lshl_add_u64 v[168:169], v[158:159], 0, s[34:35]
	v_cvt_pk_bf16_f32 v128, v108, v109
	v_cvt_pk_bf16_f32 v129, v110, v111
	v_cvt_pk_bf16_f32 v130, v104, v105
	v_cvt_pk_bf16_f32 v131, v106, v107
	v_cvt_pk_bf16_f32 v160, v100, v101
	v_cvt_pk_bf16_f32 v161, v102, v103
	v_cvt_pk_bf16_f32 v162, v96, v97
	v_cvt_pk_bf16_f32 v163, v98, v99
	s_nop 0
	global_store_dwordx4 v[168:169], v[128:131], off
	global_store_dwordx4 v[168:169], v[160:163], off offset:256
	s_mov_b64 s[34:35], 0x10000
	v_lshl_add_u64 v[170:171], v[158:159], 0, s[34:35]
	v_cvt_pk_bf16_f32 v128, v92, v93
	v_cvt_pk_bf16_f32 v129, v94, v95
	v_cvt_pk_bf16_f32 v130, v88, v89
	v_cvt_pk_bf16_f32 v131, v90, v91
	v_cvt_pk_bf16_f32 v160, v84, v85
	v_cvt_pk_bf16_f32 v161, v86, v87
	v_cvt_pk_bf16_f32 v162, v80, v81
	v_cvt_pk_bf16_f32 v163, v82, v83
	s_nop 0
	global_store_dwordx4 v[170:171], v[128:131], off
	global_store_dwordx4 v[170:171], v[160:163], off offset:256
	s_mov_b64 s[34:35], 0x18000
	v_lshl_add_u64 v[168:169], v[158:159], 0, s[34:35]
	v_cvt_pk_bf16_f32 v128, v76, v77
	v_cvt_pk_bf16_f32 v129, v78, v79
	v_cvt_pk_bf16_f32 v130, v72, v73
	v_cvt_pk_bf16_f32 v131, v74, v75
	v_cvt_pk_bf16_f32 v160, v68, v69
	v_cvt_pk_bf16_f32 v161, v70, v71
	v_cvt_pk_bf16_f32 v162, v64, v65
	v_cvt_pk_bf16_f32 v163, v66, v67
	s_nop 0
	global_store_dwordx4 v[168:169], v[128:131], off
	global_store_dwordx4 v[168:169], v[160:163], off offset:256
	s_mov_b64 s[34:35], 0x40000
	v_lshl_add_u64 v[170:171], v[158:159], 0, s[34:35]
	v_cvt_pk_bf16_f32 v128, v60, v61
	v_cvt_pk_bf16_f32 v129, v62, v63
	v_cvt_pk_bf16_f32 v130, v56, v57
	v_cvt_pk_bf16_f32 v131, v58, v59
	v_cvt_pk_bf16_f32 v160, v52, v53
	v_cvt_pk_bf16_f32 v161, v54, v55
	v_cvt_pk_bf16_f32 v162, v48, v49
	v_cvt_pk_bf16_f32 v163, v50, v51
	s_nop 0
	global_store_dwordx4 v[170:171], v[128:131], off
	global_store_dwordx4 v[170:171], v[160:163], off offset:256
	s_mov_b64 s[34:35], 0x48000
	v_lshl_add_u64 v[168:169], v[158:159], 0, s[34:35]
	v_cvt_pk_bf16_f32 v128, v44, v45
	v_cvt_pk_bf16_f32 v129, v46, v47
	v_cvt_pk_bf16_f32 v130, v40, v41
	v_cvt_pk_bf16_f32 v131, v42, v43
	v_cvt_pk_bf16_f32 v160, v36, v37
	v_cvt_pk_bf16_f32 v161, v38, v39
	v_cvt_pk_bf16_f32 v162, v32, v33
	v_cvt_pk_bf16_f32 v163, v34, v35
	s_nop 0
	global_store_dwordx4 v[168:169], v[128:131], off
	global_store_dwordx4 v[168:169], v[160:163], off offset:256
	s_mov_b64 s[34:35], 0x50000
	v_lshl_add_u64 v[170:171], v[158:159], 0, s[34:35]
	v_cvt_pk_bf16_f32 v128, v28, v29
	v_cvt_pk_bf16_f32 v129, v30, v31
	v_cvt_pk_bf16_f32 v130, v24, v25
	v_cvt_pk_bf16_f32 v131, v26, v27
	v_cvt_pk_bf16_f32 v160, v20, v21
	v_cvt_pk_bf16_f32 v161, v22, v23
	v_cvt_pk_bf16_f32 v162, v16, v17
	v_cvt_pk_bf16_f32 v163, v18, v19
	s_nop 0
	global_store_dwordx4 v[170:171], v[128:131], off
	global_store_dwordx4 v[170:171], v[160:163], off offset:256
	s_mov_b64 s[34:35], 0x58000
	v_lshl_add_u64 v[168:169], v[158:159], 0, s[34:35]
	v_cvt_pk_bf16_f32 v128, v12, v13
	v_cvt_pk_bf16_f32 v129, v14, v15
	v_cvt_pk_bf16_f32 v130, v8, v9
	v_cvt_pk_bf16_f32 v131, v10, v11
	v_cvt_pk_bf16_f32 v160, v4, v5
	v_cvt_pk_bf16_f32 v161, v6, v7
	v_cvt_pk_bf16_f32 v162, v0, v1
	v_cvt_pk_bf16_f32 v163, v2, v3
	s_nop 0
	global_store_dwordx4 v[168:169], v[128:131], off
	global_store_dwordx4 v[168:169], v[160:163], off offset:256
